# 64 blocks (8 per XCD) run the P2 conversion chunks BEFORE attention so HBM traffic overlaps the other blocks' attention; chunks de-serialised
# baseline (speedup 1.0000x reference)
; __global__ void __launch_bounds__(512) mega(Params P) {
;     ...
;   {
;     int* hs = (int*)(smem + AT_SUF + 1024 + 64);
;     unsigned* ctr = (unsigned*)(ws + WS_PTOT + 65536);
;     if (tid < 8) {
;       const float mine = P.even_b_forget[tid]; int rank = 0;
;       for (int j = 0; j < 8; ++j) { const float o = P.even_b_forget[j]; rank += (o < mine || (o == mine && j < tid)) ? 1 : 0; }
;       hs[rank] = tid;
;     }
.LBB0_150:
	s_or_b64 exec, exec, s[2:3]
	s_mov_b32 s98, 0
	s_and_b32 s99, s84, 0x18
	s_cmp_lg_u32 s99, 0
	s_cbranch_scc1 .Lp2_go
	s_mov_b32 s98, 1
	s_branch .LBB0_197
.Lp2_go:
	v_cmp_gt_u32_e32 vcc, 8, v176
	s_waitcnt lgkmcnt(0)
	s_barrier
	s_and_saveexec_b64 s[2:3], vcc
	s_cbranch_execz .LBB0_152
	v_mov_b32_e32 v177, 0
	v_lshl_add_u64 v[8:9], v[176:177], 2, s[64:65]
	global_load_dword v10, v[8:9], off
	global_load_dwordx4 v[0:3], v177, s[64:65]
	global_load_dwordx4 v[4:7], v177, s[64:65] offset:16
	v_cmp_ne_u32_e32 vcc, 0, v176
	v_cmp_lt_u32_e64 s[6:7], 1, v176
	v_cmp_lt_u32_e64 s[8:9], 2, v176
	v_cmp_lt_u32_e64 s[10:11], 3, v176
	v_cmp_lt_u32_e64 s[12:13], 4, v176
	v_cmp_lt_u32_e64 s[14:15], 5, v176
	v_cmp_eq_u32_e64 s[16:17], 7, v176
	s_add_i32 s33, 0, 0x23c40
	s_waitcnt vmcnt(1)
	v_cmp_eq_f32_e64 s[20:21], v0, v10
	v_cmp_lt_f32_e64 s[18:19], v0, v10
	v_cmp_eq_f32_e64 s[24:25], v1, v10
	s_and_b64 s[4:5], s[20:21], vcc
	v_cmp_lt_f32_e64 s[22:23], v1, v10
	v_cmp_eq_f32_e64 s[28:29], v2, v10
	s_and_b64 s[6:7], s[24:25], s[6:7]
	s_or_b64 s[4:5], s[18:19], s[4:5]
	v_cmp_lt_f32_e64 s[26:27], v2, v10
	v_cmp_eq_f32_e64 s[34:35], v3, v10
	s_and_b64 s[8:9], s[28:29], s[8:9]
	v_cndmask_b32_e64 v1, 0, 1, s[4:5]
	s_or_b64 s[4:5], s[22:23], s[6:7]
	v_cmp_lt_f32_e64 s[30:31], v3, v10
	s_waitcnt vmcnt(0)
	v_cmp_eq_f32_e64 s[38:39], v4, v10
	s_and_b64 s[10:11], s[34:35], s[10:11]
	v_cndmask_b32_e64 v2, 0, 1, s[4:5]
	s_or_b64 s[4:5], s[26:27], s[8:9]
	v_cmp_lt_f32_e64 s[36:37], v4, v10
	v_cmp_eq_f32_e64 s[42:43], v5, v10
	s_and_b64 s[12:13], s[38:39], s[12:13]
	v_cndmask_b32_e64 v3, 0, 1, s[4:5]
	s_or_b64 s[4:5], s[30:31], s[10:11]
	v_cmp_lt_f32_e64 s[40:41], v5, v10
	v_cmp_eq_f32_e64 s[46:47], v6, v10
	s_and_b64 s[14:15], s[42:43], s[14:15]
	v_cndmask_b32_e64 v4, 0, 1, s[4:5]
	s_or_b64 s[4:5], s[36:37], s[12:13]
	v_cmp_lt_f32_e64 s[44:45], v6, v10
	s_and_b64 s[16:17], s[46:47], s[16:17]
	v_cndmask_b32_e64 v5, 0, 1, s[4:5]
	s_or_b64 s[4:5], s[40:41], s[14:15]
	v_lshlrev_b32_e32 v1, 2, v1
	v_lshlrev_b32_e32 v2, 2, v2
	v_cmp_lt_f32_e64 s[48:49], v7, v10
	v_cndmask_b32_e64 v6, 0, 1, s[4:5]
	s_or_b64 s[4:5], s[44:45], s[16:17]
	v_lshlrev_b32_e32 v3, 2, v3
	v_lshlrev_b32_e32 v4, 2, v4
	v_add3_u32 v1, s33, v1, v2
	v_cndmask_b32_e64 v0, 0, 1, s[48:49]
	v_cndmask_b32_e64 v7, 0, 1, s[4:5]
	v_lshlrev_b32_e32 v5, 2, v5
	v_lshlrev_b32_e32 v6, 2, v6
	v_add3_u32 v1, v1, v3, v4
	v_lshlrev_b32_e32 v7, 2, v7
	v_add3_u32 v1, v1, v5, v6
	v_lshlrev_b32_e32 v0, 2, v0
	v_add3_u32 v0, v1, v7, v0
	ds_write_b32 v0, v176

; __global__ void __launch_bounds__(512) mega(Params P) {
;     ...
; #pragma nounroll
;     for (;;) {
;       __syncthreads();
;       if (tid == 0) hs[8] = (int)atomicAdd(ctr2, 1u);
;       __syncthreads();
;       const int c = hs[8];
;       if (c >= 2560) break;
.LBB0_209:
	s_cmp_eq_u32 s98, 1
	s_cbranch_scc0 .Lp2_conv_done
	s_mov_b32 s98, 2
	s_add_u32 s0, s82, 0x100000
	s_addc_u32 s1, s83, 0
	v_mbcnt_lo_u32_b32 v179, -1, 0
	s_branch .Lp2_go
